# same sum-of-squares v_fmac rewrite extended to the q-proj and layer-1 qkv GEMM k-loops (phases 5,10,13)
# speedup vs baseline: 1.0590x; 1.0025x over previous
; #define G_LOAD(kt_) do { \
;     if constexpr (AF32) { _Pragma("unroll") for (int i = 0; i < 4; ++i) ld16_sc1(ra[i], Af + (size_t)i * 32 * lda + (kt_) * 32); } \
;     else { _Pragma("unroll") for (int i = 0; i < 2; ++i) ld16_sc1(rab[i], Ab + (size_t)i * 64 * lda + (kt_) * 32); } \
;     _Pragma("unroll") for (int i = 0; i < 4; ++i) ld16_sc1(rb[i], Bp + (size_t)(kt_) * bstep + i * 2048); } while (0)
; template <bool AF32, class Epi>
; __device__ __forceinline__ void gemm_tile(unsigned char* smem, const void* Ap, int lda, const bf16_t* WT, int N, int K, const Epi& epi, int m0, int n0,
;                                           GPre& pr, bool preloaded, const void* nAp, int nn0, bool has_next) {
;     ...
;   for (int kt = 0; kt < nk; ++kt) {
;     const int cur = kt & 1;
;     if (kt + 1 < nk) G_STORE(cur ^ 1);
;     if (kt + 2 < nk) G_LOAD(kt + 2);
;     const bf16_t* a_s = sbase + cur * G_STAGE + (wr * 64 + l15) * GLD + quad * 8;
;     const bf16_t* b_s = sbase + cur * G_STAGE + 128 * GLD + (wc * 128 + l15) * GLD + quad * 8;
;     __builtin_amdgcn_s_setprio(1);
;     bf16x8 af[4];
; #pragma unroll
;     for (int m = 0; m < 4; ++m) af[m] = *(const bf16x8*)(a_s + m * 16 * GLD);
; #pragma unroll
;     for (int nh = 0; nh < 4; ++nh) {
;       bf16x8 bfr[2];
; #pragma unroll
;       for (int n2 = 0; n2 < 2; ++n2) bfr[n2] = *(const bf16x8*)(b_s + (nh * 2 + n2) * 16 * GLD);
; #pragma unroll
;       for (int m = 0; m < 4; ++m)
; #pragma unroll
;         for (int n2 = 0; n2 < 2; ++n2) acc[m][nh * 2 + n2] = __builtin_amdgcn_mfma_f32_16x16x32_bf16(bfr[n2], af[m], acc[m][nh * 2 + n2], 0, 0, 0);
;     }
;     __builtin_amdgcn_s_setprio(0);
;     __syncthreads();
;   }
.LBB0_296:
	s_and_b32 s3, s49, 1
	s_waitcnt vmcnt(0)
	s_xor_b32 s51, s3, 1
	s_mulk_i32 s51, 0x7800
	v_lshl_add_u32 v176, v162, 1, s51
	ds_write_b128 v176, v[0:3] offset:10240
	ds_write_b128 v176, v[4:7] offset:15360
	ds_write_b128 v176, v[8:11] offset:20480
	ds_write_b128 v176, v[12:15] offset:25600
	s_setprio 2
	global_load_dwordx4 v[0:3], v[164:165], off sc1
	v_lshl_add_u64 v[196:197], v[164:165], 0, s[20:21]
	global_load_dwordx4 v[4:7], v[196:197], off sc1
	v_lshl_add_u64 v[198:199], v[164:165], 0, s[22:23]
	global_load_dwordx4 v[8:11], v[198:199], off sc1
	v_lshl_add_u64 v[200:201], v[164:165], 0, s[24:25]
	global_load_dwordx4 v[12:15], v[200:201], off sc1
	s_setprio 0
	v_lshl_add_u32 v171, v160, 1, s51
	v_fmac_f32_e32 v187, v28, v28
	v_fmac_f32_e32 v186, v24, v24
	v_fmac_f32_e32 v183, v20, v20
	v_fmac_f32_e32 v182, v16, v16
	v_fmac_f32_e32 v187, v29, v29
	v_fmac_f32_e32 v186, v25, v25
	v_fmac_f32_e32 v183, v21, v21
	v_fmac_f32_e32 v182, v17, v17
	v_fmac_f32_e32 v187, v30, v30
	v_fmac_f32_e32 v186, v26, v26
	v_fmac_f32_e32 v183, v22, v22
	v_fmac_f32_e32 v182, v18, v18
	v_fmac_f32_e32 v187, v31, v31
	v_fmac_f32_e32 v186, v27, v27
	v_fmac_f32_e32 v183, v23, v23
	v_fmac_f32_e32 v182, v19, v19
	v_cvt_pk_bf16_f32 v202, v28, v29
	v_cvt_pk_bf16_f32 v203, v30, v31
	v_cvt_pk_bf16_f32 v24, v24, v25
	v_cvt_pk_bf16_f32 v25, v26, v27
	v_cvt_pk_bf16_f32 v26, v20, v21
	v_cvt_pk_bf16_f32 v27, v22, v23
	v_cvt_pk_bf16_f32 v16, v16, v17
	v_cvt_pk_bf16_f32 v17, v18, v19
	ds_write2st64_b64 v171, v[202:203], v[24:25] offset1:5
	ds_write2st64_b64 v171, v[26:27], v[16:17] offset0:10 offset1:15
	s_setprio 2
	global_load_dwordx4 v[28:31], v[166:167], off sc1
	v_lshl_add_u64 v[172:173], v[166:167], 0, s[14:15]
	global_load_dwordx4 v[24:27], v[172:173], off sc1
	v_lshl_add_u64 v[174:175], v[166:167], 0, s[16:17]
	global_load_dwordx4 v[20:23], v[174:175], off sc1
	v_lshl_add_u64 v[194:195], v[166:167], 0, s[18:19]
	global_load_dwordx4 v[16:19], v[194:195], off sc1
	s_setprio 0
	s_add_i32 s49, s49, 1
	s_mulk_i32 s3, 0x7800
	v_add3_u32 v171, s3, v169, v170
	s_setprio 1
	v_add3_u32 v176, s3, v168, v170
	ds_read_b128 v[172:175], v176 offset:10240
	ds_read_b128 v[194:197], v176 offset:11520
	ds_read_b128 v[198:201], v171
	ds_read_b128 v[202:205], v171 offset:1280
	ds_read_b128 v[206:209], v171 offset:2560
	ds_read_b128 v[212:215], v171 offset:3840
	s_waitcnt lgkmcnt(3)
	v_mfma_f32_16x16x32_bf16 v[156:159], v[172:175], v[198:201], v[156:159]
	v_mfma_f32_16x16x32_bf16 v[152:155], v[194:197], v[198:201], v[152:155]
	s_waitcnt lgkmcnt(2)
	v_mfma_f32_16x16x32_bf16 v[140:143], v[172:175], v[202:205], v[140:143]
	v_mfma_f32_16x16x32_bf16 v[136:139], v[194:197], v[202:205], v[136:139]
	s_waitcnt lgkmcnt(1)
	v_mfma_f32_16x16x32_bf16 v[108:111], v[172:175], v[206:209], v[108:111]
	v_mfma_f32_16x16x32_bf16 v[100:103], v[194:197], v[206:209], v[100:103]
	s_waitcnt lgkmcnt(0)
	v_mfma_f32_16x16x32_bf16 v[76:79], v[172:175], v[212:215], v[76:79]
	ds_read_b128 v[172:175], v176 offset:12800
	v_mfma_f32_16x16x32_bf16 v[68:71], v[194:197], v[212:215], v[68:71]
	ds_read_b128 v[194:197], v176 offset:14080
	s_waitcnt lgkmcnt(1)
	v_mfma_f32_16x16x32_bf16 v[148:151], v[172:175], v[198:201], v[148:151]
	s_waitcnt lgkmcnt(0)
	v_mfma_f32_16x16x32_bf16 v[144:147], v[194:197], v[198:201], v[144:147]
	v_mfma_f32_16x16x32_bf16 v[124:127], v[172:175], v[202:205], v[124:127]
	v_mfma_f32_16x16x32_bf16 v[116:119], v[194:197], v[202:205], v[116:119]
	v_mfma_f32_16x16x32_bf16 v[92:95], v[172:175], v[206:209], v[92:95]
	v_mfma_f32_16x16x32_bf16 v[84:87], v[194:197], v[206:209], v[84:87]
	v_mfma_f32_16x16x32_bf16 v[60:63], v[172:175], v[212:215], v[60:63]
	ds_read_b128 v[172:175], v176 offset:15360
	v_mfma_f32_16x16x32_bf16 v[52:55], v[194:197], v[212:215], v[52:55]
	ds_read_b128 v[194:197], v176 offset:16640
	s_waitcnt lgkmcnt(1)
	v_mfma_f32_16x16x32_bf16 v[132:135], v[172:175], v[198:201], v[132:135]
	s_waitcnt lgkmcnt(0)
	v_mfma_f32_16x16x32_bf16 v[128:131], v[194:197], v[198:201], v[128:131]
	v_mfma_f32_16x16x32_bf16 v[104:107], v[172:175], v[202:205], v[104:107]
	v_mfma_f32_16x16x32_bf16 v[96:99], v[194:197], v[202:205], v[96:99]
	v_mfma_f32_16x16x32_bf16 v[72:75], v[172:175], v[206:209], v[72:75]
	v_mfma_f32_16x16x32_bf16 v[64:67], v[194:197], v[206:209], v[64:67]
	v_mfma_f32_16x16x32_bf16 v[44:47], v[172:175], v[212:215], v[44:47]
	ds_read_b128 v[172:175], v176 offset:17920
	v_mfma_f32_16x16x32_bf16 v[40:43], v[194:197], v[212:215], v[40:43]
	ds_read_b128 v[194:197], v176 offset:19200
	s_waitcnt lgkmcnt(1)
	v_mfma_f32_16x16x32_bf16 v[120:123], v[172:175], v[198:201], v[120:123]
	s_waitcnt lgkmcnt(0)
	v_mfma_f32_16x16x32_bf16 v[112:115], v[194:197], v[198:201], v[112:115]
	v_mfma_f32_16x16x32_bf16 v[88:91], v[172:175], v[202:205], v[88:91]
	v_mfma_f32_16x16x32_bf16 v[80:83], v[194:197], v[202:205], v[80:83]
	v_mfma_f32_16x16x32_bf16 v[56:59], v[172:175], v[206:209], v[56:59]
	v_mfma_f32_16x16x32_bf16 v[48:51], v[194:197], v[206:209], v[48:51]
	v_mfma_f32_16x16x32_bf16 v[36:39], v[172:175], v[212:215], v[36:39]
	v_mfma_f32_16x16x32_bf16 v[32:35], v[194:197], v[212:215], v[32:35]
	s_setprio 0
	v_lshl_add_u64 v[164:165], v[164:165], 0, s[36:37]
	s_cmp_eq_u32 s49, 30
	v_lshl_add_u64 v[166:167], v[166:167], 0, s[26:27]
	s_barrier
	s_cbranch_scc0 .LBB0_296
; #define G_LOAD(kt_) do { \
;     if constexpr (AF32) { _Pragma("unroll") for (int i = 0; i < 4; ++i) ld16_sc1(ra[i], Af + (size_t)i * 32 * lda + (kt_) * 32); } \
;     else { _Pragma("unroll") for (int i = 0; i < 2; ++i) ld16_sc1(rab[i], Ab + (size_t)i * 64 * lda + (kt_) * 32); } \
;     _Pragma("unroll") for (int i = 0; i < 4; ++i) ld16_sc1(rb[i], Bp + (size_t)(kt_) * bstep + i * 2048); } while (0)
; template <bool AF32, class Epi>
; __device__ __forceinline__ void gemm_tile(unsigned char* smem, const void* Ap, int lda, const bf16_t* WT, int N, int K, const Epi& epi, int m0, int n0,
;                                           GPre& pr, bool preloaded, const void* nAp, int nn0, bool has_next) {
;     ...
;   if (!preloaded) G_LOAD(0);
;   G_STORE(0);
;   if (nk > 1) G_LOAD(1);
;   __syncthreads();
;   for (int kt = 0; kt < nk; ++kt) {
;     const int cur = kt & 1;
;     if (kt + 1 < nk) G_STORE(cur ^ 1);
;     if (kt + 2 < nk) G_LOAD(kt + 2);
;     const bf16_t* a_s = sbase + cur * G_STAGE + (wr * 64 + l15) * GLD + quad * 8;
;     const bf16_t* b_s = sbase + cur * G_STAGE + 128 * GLD + (wc * 128 + l15) * GLD + quad * 8;
;     __builtin_amdgcn_s_setprio(1);
;     bf16x8 af[4];
; #pragma unroll
;     for (int m = 0; m < 4; ++m) af[m] = *(const bf16x8*)(a_s + m * 16 * GLD);
; #pragma unroll
;     for (int nh = 0; nh < 4; ++nh) {
;       bf16x8 bfr[2];
; #pragma unroll
;       for (int n2 = 0; n2 < 2; ++n2) bfr[n2] = *(const bf16x8*)(b_s + (nh * 2 + n2) * 16 * GLD);
; #pragma unroll
;       for (int m = 0; m < 4; ++m)
; #pragma unroll
;         for (int n2 = 0; n2 < 2; ++n2) acc[m][nh * 2 + n2] = __builtin_amdgcn_mfma_f32_16x16x32_bf16(bfr[n2], af[m], acc[m][nh * 2 + n2], 0, 0, 0);
;     }
;     __builtin_amdgcn_s_setprio(0);
;     __syncthreads();
	s_waitcnt vmcnt(0)
	v_add_u32_e32 v176, v169, v170
	v_cvt_pk_bf16_f32 v164, v28, v29
	v_cvt_pk_bf16_f32 v165, v30, v31
	v_cvt_pk_bf16_f32 v166, v24, v25
	v_cvt_pk_bf16_f32 v167, v26, v27
	ds_write2st64_b64 v161, v[164:165], v[166:167] offset0:60 offset1:65
	v_cvt_pk_bf16_f32 v164, v20, v21
	v_cvt_pk_bf16_f32 v165, v22, v23
	v_cvt_pk_bf16_f32 v166, v16, v17
	v_cvt_pk_bf16_f32 v167, v18, v19
	ds_write2st64_b64 v161, v[164:165], v[166:167] offset0:70 offset1:75
	ds_write_b128 v163, v[0:3] offset:40960
	ds_write_b128 v163, v[4:7] offset:46080
	ds_write_b128 v163, v[8:11] offset:51200
	ds_write_b128 v163, v[12:15] offset:56320
	s_setprio 1
	v_add_u32_e32 v193, v168, v170
	ds_read_b128 v[160:163], v193 offset:10240
	ds_read_b128 v[164:167], v193 offset:11520
	ds_read_b128 v[168:171], v176
	ds_read_b128 v[172:175], v176 offset:1280
	ds_read_b128 v[194:197], v176 offset:2560
	ds_read_b128 v[198:201], v176 offset:3840
	s_waitcnt lgkmcnt(3)
	v_mfma_f32_16x16x32_bf16 v[156:159], v[160:163], v[168:171], v[156:159]
	v_mfma_f32_16x16x32_bf16 v[152:155], v[164:167], v[168:171], v[152:155]
	s_waitcnt lgkmcnt(2)
	v_mfma_f32_16x16x32_bf16 v[140:143], v[160:163], v[172:175], v[140:143]
	v_mfma_f32_16x16x32_bf16 v[136:139], v[164:167], v[172:175], v[136:139]
	s_waitcnt lgkmcnt(1)
	v_mfma_f32_16x16x32_bf16 v[108:111], v[160:163], v[194:197], v[108:111]
	v_mfma_f32_16x16x32_bf16 v[100:103], v[164:167], v[194:197], v[100:103]
	s_waitcnt lgkmcnt(0)
	v_mfma_f32_16x16x32_bf16 v[76:79], v[160:163], v[198:201], v[76:79]
	ds_read_b128 v[160:163], v193 offset:12800
	v_mfma_f32_16x16x32_bf16 v[68:71], v[164:167], v[198:201], v[68:71]
	ds_read_b128 v[164:167], v193 offset:14080
	s_waitcnt lgkmcnt(1)
	v_mfma_f32_16x16x32_bf16 v[148:151], v[160:163], v[168:171], v[148:151]
	s_waitcnt lgkmcnt(0)
	v_mfma_f32_16x16x32_bf16 v[144:147], v[164:167], v[168:171], v[144:147]
	v_mfma_f32_16x16x32_bf16 v[124:127], v[160:163], v[172:175], v[124:127]
	v_mfma_f32_16x16x32_bf16 v[116:119], v[164:167], v[172:175], v[116:119]
	v_mfma_f32_16x16x32_bf16 v[92:95], v[160:163], v[194:197], v[92:95]
	v_mfma_f32_16x16x32_bf16 v[84:87], v[164:167], v[194:197], v[84:87]
	v_mfma_f32_16x16x32_bf16 v[60:63], v[160:163], v[198:201], v[60:63]
	ds_read_b128 v[160:163], v193 offset:15360
	v_mfma_f32_16x16x32_bf16 v[52:55], v[164:167], v[198:201], v[52:55]
	ds_read_b128 v[164:167], v193 offset:16640
	s_waitcnt lgkmcnt(1)
	v_mfma_f32_16x16x32_bf16 v[212:215], v[160:163], v[194:197], v[72:75]
	s_nop 2
	ds_read_b128 v[72:75], v193 offset:19200
	s_waitcnt lgkmcnt(1)
	v_mfma_f32_16x16x32_bf16 v[216:219], v[164:167], v[194:197], v[64:67]
	s_nop 2
	ds_read_b128 v[64:67], v193 offset:17920
	v_mfma_f32_16x16x32_bf16 v[128:131], v[164:167], v[168:171], v[128:131]
	v_mfma_f32_16x16x32_bf16 v[96:99], v[164:167], v[172:175], v[96:99]
	s_waitcnt lgkmcnt(0)
	v_mfma_f32_16x16x32_bf16 v[120:123], v[64:67], v[168:171], v[120:123]
	v_mfma_f32_16x16x32_bf16 v[112:115], v[72:75], v[168:171], v[112:115]
	v_mfma_f32_16x16x32_bf16 v[88:91], v[64:67], v[172:175], v[88:91]
	v_mfma_f32_16x16x32_bf16 v[80:83], v[72:75], v[172:175], v[80:83]
	v_mfma_f32_16x16x32_bf16 v[48:51], v[72:75], v[194:197], v[48:51]
	v_mfma_f32_16x16x32_bf16 v[202:205], v[160:163], v[168:171], v[132:135]
	v_mfma_f32_16x16x32_bf16 v[206:209], v[160:163], v[172:175], v[104:107]
	v_mfma_f32_16x16x32_bf16 v[44:47], v[160:163], v[198:201], v[44:47]
	v_mfma_f32_16x16x32_bf16 v[40:43], v[164:167], v[198:201], v[40:43]
	v_mfma_f32_16x16x32_bf16 v[220:223], v[64:67], v[194:197], v[56:59]
	v_mfma_f32_16x16x32_bf16 v[36:39], v[64:67], v[198:201], v[36:39]
	v_mfma_f32_16x16x32_bf16 v[32:35], v[72:75], v[198:201], v[32:35]
	s_setprio 0
	s_barrier
; #define G_LOAD(kt_) do { \
;     if constexpr (AF32) { _Pragma("unroll") for (int i = 0; i < 4; ++i) ld16_sc1(ra[i], Af + (size_t)i * 32 * lda + (kt_) * 32); } \
;     else { _Pragma("unroll") for (int i = 0; i < 2; ++i) ld16_sc1(rab[i], Ab + (size_t)i * 64 * lda + (kt_) * 32); } \
;     _Pragma("unroll") for (int i = 0; i < 4; ++i) ld16_sc1(rb[i], Bp + (size_t)(kt_) * bstep + i * 2048); } while (0)
; template <bool AF32, class Epi>
; __device__ __forceinline__ void gemm_tile(unsigned char* smem, const void* Ap, int lda, const bf16_t* WT, int N, int K, const Epi& epi, int m0, int n0,
;                                           GPre& pr, bool preloaded, const void* nAp, int nn0, bool has_next) {
;     ...
;   for (int kt = 0; kt < nk; ++kt) {
;     const int cur = kt & 1;
;     if (kt + 1 < nk) G_STORE(cur ^ 1);
;     if (kt + 2 < nk) G_LOAD(kt + 2);
;     const bf16_t* a_s = sbase + cur * G_STAGE + (wr * 64 + l15) * GLD + quad * 8;
;     const bf16_t* b_s = sbase + cur * G_STAGE + 128 * GLD + (wc * 128 + l15) * GLD + quad * 8;
;     __builtin_amdgcn_s_setprio(1);
;     bf16x8 af[4];
; #pragma unroll
;     for (int m = 0; m < 4; ++m) af[m] = *(const bf16x8*)(a_s + m * 16 * GLD);
; #pragma unroll
;     for (int nh = 0; nh < 4; ++nh) {
;       bf16x8 bfr[2];
; #pragma unroll
;       for (int n2 = 0; n2 < 2; ++n2) bfr[n2] = *(const bf16x8*)(b_s + (nh * 2 + n2) * 16 * GLD);
; #pragma unroll
;       for (int m = 0; m < 4; ++m)
; #pragma unroll
;         for (int n2 = 0; n2 < 2; ++n2) acc[m][nh * 2 + n2] = __builtin_amdgcn_mfma_f32_16x16x32_bf16(bfr[n2], af[m], acc[m][nh * 2 + n2], 0, 0, 0);
;     }
;     __builtin_amdgcn_s_setprio(0);
;     __syncthreads();
;   }
;   if (has_next) {
;     const float* Af = (const float*)nAp + (size_t)(tid >> 3) * lda + (tid & 7) * 4;
;     const bf16_t* Ab = (const bf16_t*)nAp + (size_t)(tid >> 2) * lda + (tid & 3) * 8;
;     const bf16_t* Bp = WT + (size_t)nn0 * 32 + tid * 8;
;     G_LOAD(0);
;   }
	s_setprio 1
	ds_read_b128 v[56:59], v193 offset:40960
	ds_read_b128 v[64:67], v193 offset:42240
	ds_read_b128 v[194:197], v176 offset:30720
	ds_read_b128 v[198:201], v176 offset:32000
	ds_read_b128 v[224:227], v176 offset:33280
	ds_read_b128 v[228:231], v176 offset:34560
	s_waitcnt lgkmcnt(3)
	v_mfma_f32_16x16x32_bf16 v[172:175], v[56:59], v[194:197], v[156:159]
	v_mfma_f32_16x16x32_bf16 v[164:167], v[64:67], v[194:197], v[152:155]
	s_waitcnt lgkmcnt(2)
	v_mfma_f32_16x16x32_bf16 v[140:143], v[56:59], v[198:201], v[140:143]
	v_mfma_f32_16x16x32_bf16 v[132:135], v[64:67], v[198:201], v[136:139]
	s_waitcnt lgkmcnt(1)
	v_mfma_f32_16x16x32_bf16 v[108:111], v[56:59], v[224:227], v[108:111]
	v_mfma_f32_16x16x32_bf16 v[100:103], v[64:67], v[224:227], v[100:103]
	s_waitcnt lgkmcnt(0)
	v_mfma_f32_16x16x32_bf16 v[76:79], v[56:59], v[228:231], v[76:79]
	ds_read_b128 v[56:59], v193 offset:43520
	v_mfma_f32_16x16x32_bf16 v[72:75], v[64:67], v[228:231], v[68:71]
	ds_read_b128 v[64:67], v193 offset:44800
	s_waitcnt lgkmcnt(1)
	v_mfma_f32_16x16x32_bf16 v[168:171], v[56:59], v[194:197], v[148:151]
	s_waitcnt lgkmcnt(0)
	v_mfma_f32_16x16x32_bf16 v[156:159], v[64:67], v[194:197], v[144:147]
	v_mfma_f32_16x16x32_bf16 v[136:139], v[56:59], v[198:201], v[124:127]
	v_mfma_f32_16x16x32_bf16 v[124:127], v[64:67], v[198:201], v[116:119]
	v_mfma_f32_16x16x32_bf16 v[104:107], v[56:59], v[224:227], v[92:95]
	v_mfma_f32_16x16x32_bf16 v[92:95], v[64:67], v[224:227], v[84:87]
	v_mfma_f32_16x16x32_bf16 v[68:71], v[56:59], v[228:231], v[60:63]
	ds_read_b128 v[56:59], v193 offset:46080
	v_mfma_f32_16x16x32_bf16 v[64:67], v[64:67], v[228:231], v[52:55]
	s_nop 2
	ds_read_b128 v[52:55], v193 offset:47360
	s_waitcnt lgkmcnt(1)
	v_mfma_f32_16x16x32_bf16 v[160:163], v[56:59], v[194:197], v[202:205]
	s_waitcnt lgkmcnt(0)
	v_mfma_f32_16x16x32_bf16 v[148:151], v[52:55], v[194:197], v[128:131]
	v_mfma_f32_16x16x32_bf16 v[128:131], v[56:59], v[198:201], v[206:209]
	v_mfma_f32_16x16x32_bf16 v[116:119], v[52:55], v[198:201], v[96:99]
	v_mfma_f32_16x16x32_bf16 v[96:99], v[56:59], v[224:227], v[212:215]
	v_mfma_f32_16x16x32_bf16 v[60:63], v[56:59], v[228:231], v[44:47]
	s_nop 2
	ds_read_b128 v[44:47], v193 offset:48640
	v_mfma_f32_16x16x32_bf16 v[56:59], v[52:55], v[228:231], v[40:43]
	s_nop 2
	ds_read_b128 v[40:43], v193 offset:49920
	v_mfma_f32_16x16x32_bf16 v[84:87], v[52:55], v[224:227], v[216:219]
	s_waitcnt lgkmcnt(1)
	v_mfma_f32_16x16x32_bf16 v[152:155], v[44:47], v[194:197], v[120:123]
	s_waitcnt lgkmcnt(0)
	v_mfma_f32_16x16x32_bf16 v[144:147], v[40:43], v[194:197], v[112:115]
	v_mfma_f32_16x16x32_bf16 v[120:123], v[44:47], v[198:201], v[88:91]
	v_mfma_f32_16x16x32_bf16 v[112:115], v[40:43], v[198:201], v[80:83]
	v_mfma_f32_16x16x32_bf16 v[88:91], v[44:47], v[224:227], v[220:223]
	v_mfma_f32_16x16x32_bf16 v[80:83], v[40:43], v[224:227], v[48:51]
	v_mfma_f32_16x16x32_bf16 v[52:55], v[44:47], v[228:231], v[36:39]
	v_mfma_f32_16x16x32_bf16 v[48:51], v[40:43], v[228:231], v[32:35]
	s_and_b64 vcc, exec, s[6:7]
	s_barrier
	s_cbranch_vccz .LBB0_299
	s_ashr_i32 s51, s50, 31
	s_lshl_b64 s[6:7], s[50:51], 19
	s_add_u32 s6, s10, s6
	s_addc_u32 s7, s11, s7
	s_lshl_b32 s50, s65, 8
	v_lshl_add_u64 v[0:1], v[188:189], 2, s[6:7]
	v_lshlrev_b32_e32 v176, 2, v190
	s_ashr_i32 s51, s50, 31
	v_lshl_add_u64 v[0:1], v[0:1], 0, v[176:177]
	s_lshl_b64 s[6:7], s[50:51], 6
	global_load_dwordx4 v[40:43], v[0:1], off sc1
	s_add_u32 s6, s2, s6
	v_lshl_add_u64 v[2:3], v[0:1], 0, s[14:15]
	global_load_dwordx4 v[44:47], v[2:3], off sc1
	s_addc_u32 s7, s33, s7
	v_lshl_add_u64 v[2:3], v[0:1], 0, s[16:17]
	global_load_dwordx4 v[32:35], v[2:3], off sc1
	v_lshl_add_u64 v[0:1], v[0:1], 0, s[18:19]
	global_load_dwordx4 v[36:39], v[0:1], off sc1
	v_lshl_add_u64 v[12:13], v[184:185], 1, s[6:7]
	global_load_dwordx4 v[0:3], v[12:13], off sc1
	v_lshl_add_u64 v[4:5], v[12:13], 0, s[20:21]
	global_load_dwordx4 v[4:7], v[4:5], off sc1
	v_lshl_add_u64 v[8:9], v[12:13], 0, s[22:23]
	global_load_dwordx4 v[8:11], v[8:9], off sc1
	v_lshl_add_u64 v[12:13], v[12:13], 0, s[24:25]
	global_load_dwordx4 v[12:15], v[12:13], off sc1
	s_branch .LBB0_300

; #define G_LOAD(kt_) do { \
;     if constexpr (AF32) { _Pragma("unroll") for (int i = 0; i < 4; ++i) ld16_sc1(ra[i], Af + (size_t)i * 32 * lda + (kt_) * 32); } \
;     else { _Pragma("unroll") for (int i = 0; i < 2; ++i) ld16_sc1(rab[i], Ab + (size_t)i * 64 * lda + (kt_) * 32); } \
;     _Pragma("unroll") for (int i = 0; i < 4; ++i) ld16_sc1(rb[i], Bp + (size_t)(kt_) * bstep + i * 2048); } while (0)
; template <bool AF32, class Epi>
; __device__ __forceinline__ void gemm_tile(unsigned char* smem, const void* Ap, int lda, const bf16_t* WT, int N, int K, const Epi& epi, int m0, int n0,
;                                           GPre& pr, bool preloaded, const void* nAp, int nn0, bool has_next) {
;     ...
;   for (int kt = 0; kt < nk; ++kt) {
;     const int cur = kt & 1;
;     if (kt + 1 < nk) G_STORE(cur ^ 1);
;     if (kt + 2 < nk) G_LOAD(kt + 2);
;     const bf16_t* a_s = sbase + cur * G_STAGE + (wr * 64 + l15) * GLD + quad * 8;
;     const bf16_t* b_s = sbase + cur * G_STAGE + 128 * GLD + (wc * 128 + l15) * GLD + quad * 8;
;     __builtin_amdgcn_s_setprio(1);
;     bf16x8 af[4];
; #pragma unroll
;     for (int m = 0; m < 4; ++m) af[m] = *(const bf16x8*)(a_s + m * 16 * GLD);
; #pragma unroll
;     for (int nh = 0; nh < 4; ++nh) {
;       bf16x8 bfr[2];
; #pragma unroll
;       for (int n2 = 0; n2 < 2; ++n2) bfr[n2] = *(const bf16x8*)(b_s + (nh * 2 + n2) * 16 * GLD);
; #pragma unroll
;       for (int m = 0; m < 4; ++m)
; #pragma unroll
;         for (int n2 = 0; n2 < 2; ++n2) acc[m][nh * 2 + n2] = __builtin_amdgcn_mfma_f32_16x16x32_bf16(bfr[n2], af[m], acc[m][nh * 2 + n2], 0, 0, 0);
;     }
;     __builtin_amdgcn_s_setprio(0);
;     __syncthreads();
;   }
.LBB0_460:
	s_and_b32 s3, s51, 1
	s_waitcnt vmcnt(0)
	s_xor_b32 s53, s3, 1
	s_mulk_i32 s53, 0x7800
	v_lshl_add_u32 v176, v162, 1, s53
	ds_write_b128 v176, v[0:3] offset:10240
	ds_write_b128 v176, v[4:7] offset:15360
	ds_write_b128 v176, v[8:11] offset:20480
	ds_write_b128 v176, v[12:15] offset:25600
	s_setprio 2
	global_load_dwordx4 v[0:3], v[164:165], off sc1
	v_lshl_add_u64 v[196:197], v[164:165], 0, s[22:23]
	global_load_dwordx4 v[4:7], v[196:197], off sc1
	v_lshl_add_u64 v[198:199], v[164:165], 0, s[24:25]
	global_load_dwordx4 v[8:11], v[198:199], off sc1
	v_lshl_add_u64 v[200:201], v[164:165], 0, s[26:27]
	global_load_dwordx4 v[12:15], v[200:201], off sc1
	s_setprio 0
	v_lshl_add_u32 v171, v160, 1, s53
	v_fmac_f32_e32 v187, v28, v28
	v_fmac_f32_e32 v186, v24, v24
	v_fmac_f32_e32 v183, v20, v20
	v_fmac_f32_e32 v182, v16, v16
	v_fmac_f32_e32 v187, v29, v29
	v_fmac_f32_e32 v186, v25, v25
	v_fmac_f32_e32 v183, v21, v21
	v_fmac_f32_e32 v182, v17, v17
	v_fmac_f32_e32 v187, v30, v30
	v_fmac_f32_e32 v186, v26, v26
	v_fmac_f32_e32 v183, v22, v22
	v_fmac_f32_e32 v182, v18, v18
	v_fmac_f32_e32 v187, v31, v31
	v_fmac_f32_e32 v186, v27, v27
	v_fmac_f32_e32 v183, v23, v23
	v_fmac_f32_e32 v182, v19, v19
	v_cvt_pk_bf16_f32 v202, v28, v29
	v_cvt_pk_bf16_f32 v203, v30, v31
	v_cvt_pk_bf16_f32 v24, v24, v25
	v_cvt_pk_bf16_f32 v25, v26, v27
	v_cvt_pk_bf16_f32 v26, v20, v21
	v_cvt_pk_bf16_f32 v27, v22, v23
	v_cvt_pk_bf16_f32 v16, v16, v17
	v_cvt_pk_bf16_f32 v17, v18, v19
	ds_write2st64_b64 v171, v[202:203], v[24:25] offset1:5
	ds_write2st64_b64 v171, v[26:27], v[16:17] offset0:10 offset1:15
	s_setprio 2
	global_load_dwordx4 v[28:31], v[166:167], off sc1
	v_lshl_add_u64 v[172:173], v[166:167], 0, s[16:17]
	global_load_dwordx4 v[24:27], v[172:173], off sc1
	v_lshl_add_u64 v[174:175], v[166:167], 0, s[18:19]
	global_load_dwordx4 v[20:23], v[174:175], off sc1
	v_lshl_add_u64 v[194:195], v[166:167], 0, s[20:21]
	global_load_dwordx4 v[16:19], v[194:195], off sc1
	s_setprio 0
	s_add_i32 s51, s51, 1
	s_mulk_i32 s3, 0x7800
	v_add3_u32 v171, s3, v169, v170
	s_setprio 1
	v_add3_u32 v176, s3, v168, v170
	ds_read_b128 v[172:175], v176 offset:10240
	ds_read_b128 v[194:197], v176 offset:11520
	ds_read_b128 v[198:201], v171
	ds_read_b128 v[202:205], v171 offset:1280
	ds_read_b128 v[206:209], v171 offset:2560
	ds_read_b128 v[212:215], v171 offset:3840
	s_waitcnt lgkmcnt(3)
	v_mfma_f32_16x16x32_bf16 v[156:159], v[172:175], v[198:201], v[156:159]
	v_mfma_f32_16x16x32_bf16 v[152:155], v[194:197], v[198:201], v[152:155]
	s_waitcnt lgkmcnt(2)
	v_mfma_f32_16x16x32_bf16 v[140:143], v[172:175], v[202:205], v[140:143]
	v_mfma_f32_16x16x32_bf16 v[136:139], v[194:197], v[202:205], v[136:139]
	s_waitcnt lgkmcnt(1)
	v_mfma_f32_16x16x32_bf16 v[108:111], v[172:175], v[206:209], v[108:111]
	v_mfma_f32_16x16x32_bf16 v[100:103], v[194:197], v[206:209], v[100:103]
	s_waitcnt lgkmcnt(0)
	v_mfma_f32_16x16x32_bf16 v[76:79], v[172:175], v[212:215], v[76:79]
	ds_read_b128 v[172:175], v176 offset:12800
	v_mfma_f32_16x16x32_bf16 v[68:71], v[194:197], v[212:215], v[68:71]
	ds_read_b128 v[194:197], v176 offset:14080
	s_waitcnt lgkmcnt(1)
	v_mfma_f32_16x16x32_bf16 v[148:151], v[172:175], v[198:201], v[148:151]
	s_waitcnt lgkmcnt(0)
	v_mfma_f32_16x16x32_bf16 v[144:147], v[194:197], v[198:201], v[144:147]
	v_mfma_f32_16x16x32_bf16 v[124:127], v[172:175], v[202:205], v[124:127]
	v_mfma_f32_16x16x32_bf16 v[116:119], v[194:197], v[202:205], v[116:119]
	v_mfma_f32_16x16x32_bf16 v[92:95], v[172:175], v[206:209], v[92:95]
	v_mfma_f32_16x16x32_bf16 v[84:87], v[194:197], v[206:209], v[84:87]
	v_mfma_f32_16x16x32_bf16 v[60:63], v[172:175], v[212:215], v[60:63]
	ds_read_b128 v[172:175], v176 offset:15360
	v_mfma_f32_16x16x32_bf16 v[52:55], v[194:197], v[212:215], v[52:55]
	ds_read_b128 v[194:197], v176 offset:16640
	s_waitcnt lgkmcnt(1)
	v_mfma_f32_16x16x32_bf16 v[132:135], v[172:175], v[198:201], v[132:135]
	s_waitcnt lgkmcnt(0)
	v_mfma_f32_16x16x32_bf16 v[128:131], v[194:197], v[198:201], v[128:131]
	v_mfma_f32_16x16x32_bf16 v[104:107], v[172:175], v[202:205], v[104:107]
	v_mfma_f32_16x16x32_bf16 v[96:99], v[194:197], v[202:205], v[96:99]
	v_mfma_f32_16x16x32_bf16 v[72:75], v[172:175], v[206:209], v[72:75]
	v_mfma_f32_16x16x32_bf16 v[64:67], v[194:197], v[206:209], v[64:67]
	v_mfma_f32_16x16x32_bf16 v[44:47], v[172:175], v[212:215], v[44:47]
	ds_read_b128 v[172:175], v176 offset:17920
	v_mfma_f32_16x16x32_bf16 v[40:43], v[194:197], v[212:215], v[40:43]
	ds_read_b128 v[194:197], v176 offset:19200
	s_waitcnt lgkmcnt(1)
	v_mfma_f32_16x16x32_bf16 v[120:123], v[172:175], v[198:201], v[120:123]
	s_waitcnt lgkmcnt(0)
	v_mfma_f32_16x16x32_bf16 v[112:115], v[194:197], v[198:201], v[112:115]
	v_mfma_f32_16x16x32_bf16 v[88:91], v[172:175], v[202:205], v[88:91]
	v_mfma_f32_16x16x32_bf16 v[80:83], v[194:197], v[202:205], v[80:83]
	v_mfma_f32_16x16x32_bf16 v[56:59], v[172:175], v[206:209], v[56:59]
	v_mfma_f32_16x16x32_bf16 v[48:51], v[194:197], v[206:209], v[48:51]
	v_mfma_f32_16x16x32_bf16 v[36:39], v[172:175], v[212:215], v[36:39]
	v_mfma_f32_16x16x32_bf16 v[32:35], v[194:197], v[212:215], v[32:35]
	s_setprio 0
	v_lshl_add_u64 v[164:165], v[164:165], 0, s[38:39]
	s_cmp_eq_u32 s51, 30
	v_lshl_add_u64 v[166:167], v[166:167], 0, s[28:29]
	s_barrier
	s_cbranch_scc0 .LBB0_460
; #define G_LOAD(kt_) do { \
;     if constexpr (AF32) { _Pragma("unroll") for (int i = 0; i < 4; ++i) ld16_sc1(ra[i], Af + (size_t)i * 32 * lda + (kt_) * 32); } \
;     else { _Pragma("unroll") for (int i = 0; i < 2; ++i) ld16_sc1(rab[i], Ab + (size_t)i * 64 * lda + (kt_) * 32); } \
;     _Pragma("unroll") for (int i = 0; i < 4; ++i) ld16_sc1(rb[i], Bp + (size_t)(kt_) * bstep + i * 2048); } while (0)
; template <bool AF32, class Epi>
; __device__ __forceinline__ void gemm_tile(unsigned char* smem, const void* Ap, int lda, const bf16_t* WT, int N, int K, const Epi& epi, int m0, int n0,
;                                           GPre& pr, bool preloaded, const void* nAp, int nn0, bool has_next) {
;     ...
;   if (!preloaded) G_LOAD(0);
;   G_STORE(0);
;   if (nk > 1) G_LOAD(1);
;   __syncthreads();
;   for (int kt = 0; kt < nk; ++kt) {
;     const int cur = kt & 1;
;     if (kt + 1 < nk) G_STORE(cur ^ 1);
;     if (kt + 2 < nk) G_LOAD(kt + 2);
;     const bf16_t* a_s = sbase + cur * G_STAGE + (wr * 64 + l15) * GLD + quad * 8;
;     const bf16_t* b_s = sbase + cur * G_STAGE + 128 * GLD + (wc * 128 + l15) * GLD + quad * 8;
;     __builtin_amdgcn_s_setprio(1);
;     bf16x8 af[4];
; #pragma unroll
;     for (int m = 0; m < 4; ++m) af[m] = *(const bf16x8*)(a_s + m * 16 * GLD);
; #pragma unroll
;     for (int nh = 0; nh < 4; ++nh) {
;       bf16x8 bfr[2];
; #pragma unroll
;       for (int n2 = 0; n2 < 2; ++n2) bfr[n2] = *(const bf16x8*)(b_s + (nh * 2 + n2) * 16 * GLD);
; #pragma unroll
;       for (int m = 0; m < 4; ++m)
; #pragma unroll
;         for (int n2 = 0; n2 < 2; ++n2) acc[m][nh * 2 + n2] = __builtin_amdgcn_mfma_f32_16x16x32_bf16(bfr[n2], af[m], acc[m][nh * 2 + n2], 0, 0, 0);
;     }
;     __builtin_amdgcn_s_setprio(0);
;     __syncthreads();
	s_waitcnt vmcnt(0)
	v_add_u32_e32 v176, v169, v170
	v_cvt_pk_bf16_f32 v164, v28, v29
	v_cvt_pk_bf16_f32 v165, v30, v31
	v_cvt_pk_bf16_f32 v166, v24, v25
	v_cvt_pk_bf16_f32 v167, v26, v27
	ds_write2st64_b64 v161, v[164:165], v[166:167] offset0:60 offset1:65
	v_cvt_pk_bf16_f32 v164, v20, v21
	v_cvt_pk_bf16_f32 v165, v22, v23
	v_cvt_pk_bf16_f32 v166, v16, v17
	v_cvt_pk_bf16_f32 v167, v18, v19
	ds_write2st64_b64 v161, v[164:165], v[166:167] offset0:70 offset1:75
	ds_write_b128 v163, v[0:3] offset:40960
	ds_write_b128 v163, v[4:7] offset:46080
	ds_write_b128 v163, v[8:11] offset:51200
	ds_write_b128 v163, v[12:15] offset:56320
	s_setprio 1
	v_add_u32_e32 v193, v168, v170
	ds_read_b128 v[160:163], v193 offset:10240
	ds_read_b128 v[164:167], v193 offset:11520
	ds_read_b128 v[168:171], v176
	ds_read_b128 v[172:175], v176 offset:1280
	ds_read_b128 v[194:197], v176 offset:2560
	ds_read_b128 v[198:201], v176 offset:3840
	s_waitcnt lgkmcnt(3)
	v_mfma_f32_16x16x32_bf16 v[156:159], v[160:163], v[168:171], v[156:159]
	v_mfma_f32_16x16x32_bf16 v[152:155], v[164:167], v[168:171], v[152:155]
	s_waitcnt lgkmcnt(2)
	v_mfma_f32_16x16x32_bf16 v[140:143], v[160:163], v[172:175], v[140:143]
	v_mfma_f32_16x16x32_bf16 v[136:139], v[164:167], v[172:175], v[136:139]
	s_waitcnt lgkmcnt(1)
	v_mfma_f32_16x16x32_bf16 v[108:111], v[160:163], v[194:197], v[108:111]
	v_mfma_f32_16x16x32_bf16 v[100:103], v[164:167], v[194:197], v[100:103]
	s_waitcnt lgkmcnt(0)
	v_mfma_f32_16x16x32_bf16 v[76:79], v[160:163], v[198:201], v[76:79]
	ds_read_b128 v[160:163], v193 offset:12800
	v_mfma_f32_16x16x32_bf16 v[68:71], v[164:167], v[198:201], v[68:71]
	ds_read_b128 v[164:167], v193 offset:14080
	s_waitcnt lgkmcnt(1)
	v_mfma_f32_16x16x32_bf16 v[148:151], v[160:163], v[168:171], v[148:151]
	s_waitcnt lgkmcnt(0)
	v_mfma_f32_16x16x32_bf16 v[144:147], v[164:167], v[168:171], v[144:147]
	v_mfma_f32_16x16x32_bf16 v[124:127], v[160:163], v[172:175], v[124:127]
	v_mfma_f32_16x16x32_bf16 v[116:119], v[164:167], v[172:175], v[116:119]
	v_mfma_f32_16x16x32_bf16 v[92:95], v[160:163], v[194:197], v[92:95]
	v_mfma_f32_16x16x32_bf16 v[84:87], v[164:167], v[194:197], v[84:87]
	v_mfma_f32_16x16x32_bf16 v[60:63], v[160:163], v[198:201], v[60:63]
	ds_read_b128 v[160:163], v193 offset:15360
	v_mfma_f32_16x16x32_bf16 v[52:55], v[164:167], v[198:201], v[52:55]
	ds_read_b128 v[164:167], v193 offset:16640
	s_waitcnt lgkmcnt(1)
	v_mfma_f32_16x16x32_bf16 v[212:215], v[160:163], v[194:197], v[72:75]
	s_nop 2
	ds_read_b128 v[72:75], v193 offset:19200
	s_waitcnt lgkmcnt(1)
	v_mfma_f32_16x16x32_bf16 v[216:219], v[164:167], v[194:197], v[64:67]
	s_nop 2
	ds_read_b128 v[64:67], v193 offset:17920
	v_mfma_f32_16x16x32_bf16 v[128:131], v[164:167], v[168:171], v[128:131]
	v_mfma_f32_16x16x32_bf16 v[96:99], v[164:167], v[172:175], v[96:99]
	s_waitcnt lgkmcnt(0)
	v_mfma_f32_16x16x32_bf16 v[120:123], v[64:67], v[168:171], v[120:123]
	v_mfma_f32_16x16x32_bf16 v[112:115], v[72:75], v[168:171], v[112:115]
	v_mfma_f32_16x16x32_bf16 v[88:91], v[64:67], v[172:175], v[88:91]
	v_mfma_f32_16x16x32_bf16 v[80:83], v[72:75], v[172:175], v[80:83]
	v_mfma_f32_16x16x32_bf16 v[48:51], v[72:75], v[194:197], v[48:51]
	v_mfma_f32_16x16x32_bf16 v[202:205], v[160:163], v[168:171], v[132:135]
	v_mfma_f32_16x16x32_bf16 v[206:209], v[160:163], v[172:175], v[104:107]
	v_mfma_f32_16x16x32_bf16 v[44:47], v[160:163], v[198:201], v[44:47]
	v_mfma_f32_16x16x32_bf16 v[40:43], v[164:167], v[198:201], v[40:43]
	v_mfma_f32_16x16x32_bf16 v[220:223], v[64:67], v[194:197], v[56:59]
	v_mfma_f32_16x16x32_bf16 v[36:39], v[64:67], v[198:201], v[36:39]
	v_mfma_f32_16x16x32_bf16 v[32:35], v[72:75], v[198:201], v[32:35]
	s_setprio 0
	s_barrier
; #define G_LOAD(kt_) do { \
;     if constexpr (AF32) { _Pragma("unroll") for (int i = 0; i < 4; ++i) ld16_sc1(ra[i], Af + (size_t)i * 32 * lda + (kt_) * 32); } \
;     else { _Pragma("unroll") for (int i = 0; i < 2; ++i) ld16_sc1(rab[i], Ab + (size_t)i * 64 * lda + (kt_) * 32); } \
;     _Pragma("unroll") for (int i = 0; i < 4; ++i) ld16_sc1(rb[i], Bp + (size_t)(kt_) * bstep + i * 2048); } while (0)
; template <bool AF32, class Epi>
; __device__ __forceinline__ void gemm_tile(unsigned char* smem, const void* Ap, int lda, const bf16_t* WT, int N, int K, const Epi& epi, int m0, int n0,
;                                           GPre& pr, bool preloaded, const void* nAp, int nn0, bool has_next) {
;     ...
;   for (int kt = 0; kt < nk; ++kt) {
;     const int cur = kt & 1;
;     if (kt + 1 < nk) G_STORE(cur ^ 1);
;     if (kt + 2 < nk) G_LOAD(kt + 2);
;     const bf16_t* a_s = sbase + cur * G_STAGE + (wr * 64 + l15) * GLD + quad * 8;
;     const bf16_t* b_s = sbase + cur * G_STAGE + 128 * GLD + (wc * 128 + l15) * GLD + quad * 8;
;     __builtin_amdgcn_s_setprio(1);
;     bf16x8 af[4];
; #pragma unroll
;     for (int m = 0; m < 4; ++m) af[m] = *(const bf16x8*)(a_s + m * 16 * GLD);
; #pragma unroll
;     for (int nh = 0; nh < 4; ++nh) {
;       bf16x8 bfr[2];
; #pragma unroll
;       for (int n2 = 0; n2 < 2; ++n2) bfr[n2] = *(const bf16x8*)(b_s + (nh * 2 + n2) * 16 * GLD);
; #pragma unroll
;       for (int m = 0; m < 4; ++m)
; #pragma unroll
;         for (int n2 = 0; n2 < 2; ++n2) acc[m][nh * 2 + n2] = __builtin_amdgcn_mfma_f32_16x16x32_bf16(bfr[n2], af[m], acc[m][nh * 2 + n2], 0, 0, 0);
;     }
;     __builtin_amdgcn_s_setprio(0);
;     __syncthreads();
;   }
;   if (has_next) {
;     const float* Af = (const float*)nAp + (size_t)(tid >> 3) * lda + (tid & 7) * 4;
;     const bf16_t* Ab = (const bf16_t*)nAp + (size_t)(tid >> 2) * lda + (tid & 3) * 8;
;     const bf16_t* Bp = WT + (size_t)nn0 * 32 + tid * 8;
;     G_LOAD(0);
;   }
	s_setprio 1
	ds_read_b128 v[56:59], v193 offset:40960
	ds_read_b128 v[64:67], v193 offset:42240
	ds_read_b128 v[194:197], v176 offset:30720
	ds_read_b128 v[198:201], v176 offset:32000
	ds_read_b128 v[224:227], v176 offset:33280
	ds_read_b128 v[228:231], v176 offset:34560
	s_waitcnt lgkmcnt(3)
	v_mfma_f32_16x16x32_bf16 v[172:175], v[56:59], v[194:197], v[156:159]
	v_mfma_f32_16x16x32_bf16 v[164:167], v[64:67], v[194:197], v[152:155]
	s_waitcnt lgkmcnt(2)
	v_mfma_f32_16x16x32_bf16 v[140:143], v[56:59], v[198:201], v[140:143]
	v_mfma_f32_16x16x32_bf16 v[132:135], v[64:67], v[198:201], v[136:139]
	s_waitcnt lgkmcnt(1)
	v_mfma_f32_16x16x32_bf16 v[108:111], v[56:59], v[224:227], v[108:111]
	v_mfma_f32_16x16x32_bf16 v[100:103], v[64:67], v[224:227], v[100:103]
	s_waitcnt lgkmcnt(0)
	v_mfma_f32_16x16x32_bf16 v[76:79], v[56:59], v[228:231], v[76:79]
	ds_read_b128 v[56:59], v193 offset:43520
	v_mfma_f32_16x16x32_bf16 v[72:75], v[64:67], v[228:231], v[68:71]
	ds_read_b128 v[64:67], v193 offset:44800
	s_waitcnt lgkmcnt(1)
	v_mfma_f32_16x16x32_bf16 v[168:171], v[56:59], v[194:197], v[148:151]
	s_waitcnt lgkmcnt(0)
	v_mfma_f32_16x16x32_bf16 v[156:159], v[64:67], v[194:197], v[144:147]
	v_mfma_f32_16x16x32_bf16 v[136:139], v[56:59], v[198:201], v[124:127]
	v_mfma_f32_16x16x32_bf16 v[124:127], v[64:67], v[198:201], v[116:119]
	v_mfma_f32_16x16x32_bf16 v[104:107], v[56:59], v[224:227], v[92:95]
	v_mfma_f32_16x16x32_bf16 v[92:95], v[64:67], v[224:227], v[84:87]
	v_mfma_f32_16x16x32_bf16 v[68:71], v[56:59], v[228:231], v[60:63]
	ds_read_b128 v[56:59], v193 offset:46080
	v_mfma_f32_16x16x32_bf16 v[64:67], v[64:67], v[228:231], v[52:55]
	s_nop 2
	ds_read_b128 v[52:55], v193 offset:47360
	s_waitcnt lgkmcnt(1)
	v_mfma_f32_16x16x32_bf16 v[160:163], v[56:59], v[194:197], v[202:205]
	s_waitcnt lgkmcnt(0)
	v_mfma_f32_16x16x32_bf16 v[148:151], v[52:55], v[194:197], v[128:131]
	v_mfma_f32_16x16x32_bf16 v[128:131], v[56:59], v[198:201], v[206:209]
	v_mfma_f32_16x16x32_bf16 v[116:119], v[52:55], v[198:201], v[96:99]
	v_mfma_f32_16x16x32_bf16 v[96:99], v[56:59], v[224:227], v[212:215]
	v_mfma_f32_16x16x32_bf16 v[60:63], v[56:59], v[228:231], v[44:47]
	s_nop 2
	ds_read_b128 v[44:47], v193 offset:48640
	v_mfma_f32_16x16x32_bf16 v[56:59], v[52:55], v[228:231], v[40:43]
	s_nop 2
	ds_read_b128 v[40:43], v193 offset:49920
	v_mfma_f32_16x16x32_bf16 v[84:87], v[52:55], v[224:227], v[216:219]
	s_waitcnt lgkmcnt(1)
	v_mfma_f32_16x16x32_bf16 v[152:155], v[44:47], v[194:197], v[120:123]
	s_waitcnt lgkmcnt(0)
	v_mfma_f32_16x16x32_bf16 v[144:147], v[40:43], v[194:197], v[112:115]
	v_mfma_f32_16x16x32_bf16 v[120:123], v[44:47], v[198:201], v[88:91]
	v_mfma_f32_16x16x32_bf16 v[112:115], v[40:43], v[198:201], v[80:83]
	v_mfma_f32_16x16x32_bf16 v[88:91], v[44:47], v[224:227], v[220:223]
	v_mfma_f32_16x16x32_bf16 v[80:83], v[40:43], v[224:227], v[48:51]
	v_mfma_f32_16x16x32_bf16 v[52:55], v[44:47], v[228:231], v[36:39]
	v_mfma_f32_16x16x32_bf16 v[48:51], v[40:43], v[228:231], v[32:35]
	s_and_b64 vcc, exec, s[6:7]
	s_barrier
	s_cbranch_vccz .LBB0_463
	s_ashr_i32 s53, s52, 31
	s_lshl_b64 s[6:7], s[52:53], 19
	s_add_u32 s6, s12, s6
	s_addc_u32 s7, s13, s7
	s_lshl_b32 s52, s68, 8
	v_lshl_add_u64 v[0:1], v[188:189], 2, s[6:7]
	v_lshlrev_b32_e32 v176, 2, v190
	s_ashr_i32 s53, s52, 31
	v_lshl_add_u64 v[0:1], v[0:1], 0, v[176:177]
	s_lshl_b64 s[6:7], s[52:53], 6
	global_load_dwordx4 v[40:43], v[0:1], off sc1
	s_add_u32 s6, s2, s6
	v_lshl_add_u64 v[2:3], v[0:1], 0, s[16:17]
	global_load_dwordx4 v[44:47], v[2:3], off sc1
	s_addc_u32 s7, s33, s7
	v_lshl_add_u64 v[2:3], v[0:1], 0, s[18:19]
	global_load_dwordx4 v[32:35], v[2:3], off sc1
	v_lshl_add_u64 v[0:1], v[0:1], 0, s[20:21]
	global_load_dwordx4 v[36:39], v[0:1], off sc1
	v_lshl_add_u64 v[12:13], v[184:185], 1, s[6:7]
	global_load_dwordx4 v[0:3], v[12:13], off sc1
	v_lshl_add_u64 v[4:5], v[12:13], 0, s[22:23]
	global_load_dwordx4 v[4:7], v[4:5], off sc1
	v_lshl_add_u64 v[8:9], v[12:13], 0, s[24:25]
	global_load_dwordx4 v[8:11], v[8:9], off sc1
	v_lshl_add_u64 v[12:13], v[12:13], 0, s[26:27]
	global_load_dwordx4 v[12:15], v[12:13], off sc1
	s_branch .LBB0_464
